# EVMIX: unit->part mapping rotated by round so every workgroup gets a mix of conv and pool parts (balance)
# speedup vs baseline: 1.0186x; 1.0186x over previous
; __device__ __forceinline__ void phase_evmix(const Params& p, unsigned char* lds, int e) {
;     ...
;         const int part = u & 7, rt = u >> 3; const int t0 = rt * 128; const int pos0 = t0 & (SEQ - 1);
;         __syncthreads();
;         if (part < 4) {
;     ...
;             const int g = part - 4, win = 2 << g;
;             if (g != gl) {
;                 const bf16_t* Bt = poolT + (size_t)g * 128 * 128;
; #pragma unroll
;                 for (int k = 0; k < 4; ++k) { const int it = tid + k * NTHREADS; const int n = it >> 4, ch = it & 15; *(u32x4*)(Bl + n * 136 + ch * 8) = *(const u32x4*)(Bt + (size_t)n * 128 + ch * 8); }
;                 gl = g; }
.LBB0_915:
	s_lshl_b32 s4, s44, 4
	s_lshr_b32 s45, s44, 8
	s_add_i32 s45, s45, s44
	s_and_b32 s45, s45, 7
	s_and_b32 s42, s4, 0xffffff80
	s_mov_b64 s[36:37], -1
	s_cmp_gt_u32 s45, 3
	v_readfirstlane_b32 s43, v0
	s_waitcnt vmcnt(0)
	s_barrier
	s_cbranch_scc0 .LBB0_958
	s_add_i32 s36, s45, -4
	v_cmp_eq_u32_e32 vcc, s36, v212
	v_mov_b32_e32 v213, v212
	s_cbranch_vccnz .LBB0_918
	s_mov_b32 s37, s75
	s_lshl_b64 s[38:39], s[36:37], 15
	v_lshl_add_u64 v[2:3], v[150:151], 0, s[38:39]
	v_lshl_add_u64 v[60:61], v[2:3], 0, v[158:159]
	global_load_dwordx4 v[60:63], v[60:61], off
	v_add_u32_e32 v1, v149, v157
	v_mov_b32_e32 v213, s36
	s_waitcnt vmcnt(0)
	ds_write_b128 v1, v[60:63]
	v_lshl_add_u64 v[60:61], v[2:3], 0, v[162:163]
	global_load_dwordx4 v[60:63], v[60:61], off
	v_add_u32_e32 v1, v149, v161
	s_waitcnt vmcnt(0)
	ds_write_b128 v1, v[60:63]
	v_lshl_add_u64 v[60:61], v[2:3], 0, v[166:167]
	global_load_dwordx4 v[60:63], v[60:61], off
	v_add_u32_e32 v1, v149, v165
	v_lshl_add_u64 v[2:3], v[2:3], 0, v[222:223]
	s_waitcnt vmcnt(0)
	ds_write_b128 v1, v[60:63]
	global_load_dwordx4 v[60:63], v[2:3], off
	v_add_u32_e32 v1, v149, v169
	s_waitcnt vmcnt(0)
	ds_write_b128 v1, v[60:63]

; __device__ __forceinline__ void phase_evmix(const Params& p, unsigned char* lds, int e) {
;     ...
;             u32x4 gb[4];
; #pragma unroll
;             for (int k = 0; k < 4; ++k) gb[k] = pg[k];
;             if (u + G < NU) EV_LOAD(u + G);
.LBB0_924:
	s_or_b64 exec, exec, s[38:39]
	s_add_i32 s43, s44, s78
	v_mov_b64_e32 v[62:63], v[58:59]
	v_mov_b64_e32 v[66:67], v[54:55]
	v_mov_b64_e32 v[70:71], v[46:47]
	v_mov_b64_e32 v[74:75], v[34:35]
	v_mov_b64_e32 v[130:131], v[18:19]
	v_mov_b64_e32 v[126:127], v[14:15]
	v_mov_b64_e32 v[138:139], v[30:31]
	v_mov_b64_e32 v[142:143], v[38:39]
	v_mov_b64_e32 v[146:147], v[42:43]
	s_cmpk_gt_i32 s43, 0x7ff
	v_mov_b64_e32 v[60:61], v[56:57]
	v_mov_b64_e32 v[64:65], v[52:53]
	v_mov_b64_e32 v[68:69], v[44:45]
	v_mov_b64_e32 v[72:73], v[32:33]
	v_mov_b64_e32 v[128:129], v[16:17]
	v_mov_b64_e32 v[124:125], v[12:13]
	v_mov_b64_e32 v[136:137], v[28:29]
	v_mov_b64_e32 v[140:141], v[36:37]
	v_mov_b64_e32 v[144:145], v[40:41]
	v_mov_b32_e32 v80, v4
	v_mov_b32_e32 v81, v5
	v_mov_b32_e32 v82, v6
	v_mov_b32_e32 v83, v7
	v_mov_b32_e32 v76, v8
	v_mov_b32_e32 v77, v9
	v_mov_b32_e32 v78, v10
	v_mov_b32_e32 v79, v11
	v_mov_b32_e32 v120, v24
	v_mov_b32_e32 v121, v25
	v_mov_b32_e32 v122, v26
	v_mov_b32_e32 v123, v27
	v_mov_b32_e32 v112, v20
	v_mov_b32_e32 v113, v21
	v_mov_b32_e32 v114, v22
	v_mov_b32_e32 v115, v23
	v_mov_b32_e32 v132, v48
	v_mov_b32_e32 v133, v49
	v_mov_b32_e32 v134, v50
	v_mov_b32_e32 v135, v51
	s_cbranch_scc1 .LBB0_949
	s_lshr_b32 s38, s43, 8
	s_add_i32 s38, s38, s43
	s_and_b32 s38, s38, 7
	s_lshl_b32 s33, s43, 4
	s_and_b32 s5, s33, 0xffffff80
	s_and_b32 s37, s33, 0xf80
	s_lshl_b32 s33, s38, 7
	s_cmp_gt_u32 s38, 3
	s_mov_b64 s[38:39], -1
	s_cbranch_scc0 .LBB0_937
	s_sub_i32 s47, 14, s37
	s_add_i32 s46, s5, -15
	s_lshl_b32 s38, s33, 1
	s_add_u32 s38, s26, s38
	v_cmp_lt_i32_e32 vcc, s47, v156
	s_addc_u32 s39, s27, 0
	s_and_b64 s[48:49], s[6:7], vcc
	v_mov_b32_e32 v76, 0
	v_mov_b32_e32 v80, 0
	v_mov_b32_e32 v81, 0
	v_mov_b32_e32 v82, 0
	v_mov_b32_e32 v83, 0
	s_and_saveexec_b64 s[40:41], s[48:49]
	s_cbranch_execz .LBB0_928
	v_add_u32_e32 v2, s46, v156
	v_ashrrev_i32_e32 v3, 31, v2
	v_lshlrev_b64 v[2:3], 12, v[2:3]
	v_lshl_add_u64 v[2:3], s[38:39], 0, v[2:3]
	v_lshlrev_b32_e32 v60, 1, v148
	v_mov_b32_e32 v61, v0
	v_lshl_add_u64 v[2:3], v[2:3], 0, v[60:61]
	global_load_dwordx4 v[80:83], v[2:3], off offset:2048

.LBB0_974:
	s_lshr_b32 s36, s43, 8
	s_add_i32 s36, s36, s43
	s_and_b32 s36, s36, 7
	s_lshl_b32 s5, s43, 4
	s_and_b32 s4, s5, 0xffffff80
	s_and_b32 s33, s5, 0xf80
	s_lshl_b32 s5, s36, 7
	s_cmp_gt_u32 s36, 3
	s_mov_b64 s[36:37], -1
	s_cbranch_scc0 .LBB0_986
	s_sub_i32 s41, 14, s33
	s_add_i32 s40, s4, -15
	s_lshl_b32 s36, s5, 1
	s_add_u32 s36, s26, s36
	v_cmp_lt_i32_e32 vcc, s41, v156
	s_addc_u32 s37, s27, 0
	s_and_b64 s[44:45], s[6:7], vcc
	v_mov_b32_e32 v8, 0
	v_mov_b32_e32 v4, 0
	v_mov_b32_e32 v5, 0
	v_mov_b32_e32 v6, 0
	v_mov_b32_e32 v7, 0
	s_and_saveexec_b64 s[38:39], s[44:45]
	s_cbranch_execz .LBB0_977
	v_add_u32_e32 v2, s40, v156
	v_ashrrev_i32_e32 v3, 31, v2
	v_lshlrev_b64 v[2:3], 12, v[2:3]
	v_lshl_add_u64 v[2:3], s[36:37], 0, v[2:3]
	v_lshlrev_b32_e32 v4, 1, v148
	v_mov_b32_e32 v5, v0
	v_lshl_add_u64 v[2:3], v[2:3], 0, v[4:5]
	global_load_dwordx4 v[4:7], v[2:3], off offset:2048
